# attn loop: deep LDS prefetch ring + static prio for waves 4-7 via scalar branch (baseline's exec-masked setprio gave all waves prio 2)
# speedup vs baseline: 1.0076x; 1.0076x over previous
; __device__ __forceinline__ int v_st(int k, int c) { const int kk = (k & ~0xC) | ((k & 4) << 1) | ((k & 8) >> 1); return ((kk >> 3) * 4 + (c >> 5)) * 512 + ((kk & 7) * 32 + (c & 31)) * 2; }
; __device__ __forceinline__ int v_rd_base(int lane) { return ((lane & 3) << 3) | (((lane >> 2) & 3) << 6) | (((lane >> 4) & 1) << 5) | (((lane >> 5) & 1) << 8); }
; #define LBAR() do { asm volatile("s_waitcnt lgkmcnt(0)" ::: "memory"); __builtin_amdgcn_s_barrier(); asm volatile("" ::: "memory"); } while (0)
; __device__ __forceinline__ void attn_unit(const bf16_t* __restrict__ Qb, const bf16_t* __restrict__ Kn, const bf16_t* __restrict__ Vh, const bf16_t* __restrict__ Kr,
;                                           bf16_t* GO, int seq, char* lds, const int tid) {
;   const int wid = tid >> 6, lane = tid & 63, r32 = lane & 31, hi = lane >> 5;
;   char* V_lds = lds; char* K_lds = lds + 3 * SHM_V;
;   float* ws = (float*)(lds + 3 * SHM_V + 3 * SHM_K) + wid * 64; float* li_l = ws; float* al_l = ws + 32;
;   if (wid < 4) __builtin_amdgcn_s_setprio(2); else __builtin_amdgcn_s_setprio(0);
;   float m_reg = -1e30f, l_reg = 0; f32x16 o[4] = {}; bf16x8 qr[8];
;   char* qrl = lds + 3 * SHM_V + 3 * SHM_K + NW * 64 * 4 + wid * 4096 + r32 * 128;
;   const bf16_t* Qw = Qb + (long)(wid * QBLK + r32) * LDQ + hi * 8;
; #pragma unroll
;   for (int d0 = 0; d0 < 8; ++d0) qr[d0] = *reinterpret_cast<const bf16x8*>(Qw + d0 * 16);
; #pragma unroll
;   for (int d0 = 8; d0 < 12; ++d0) *reinterpret_cast<bf16x8*>(qrl + (((2 * (d0 - 8) + hi) ^ ((r32 >> 1) & 7)) << 4)) = *reinterpret_cast<const bf16x8*>(Qw + d0 * 16);
;   const int sr = tid >> 4, sc = (tid & 15) * 8, vst0 = v_st(sr, sc), vst1 = v_st(32 + sr, sc);
;   const int rr = tid >> 3, rc = (tid & 7) * 8;
;   const int vb0 = (int)(uintptr_t)V_lds + v_rd_base(lane);
;   const unsigned offkv = (unsigned)(sr * LDKV + sc) * 2u, offkr = (unsigned)(rr * LDKR + rc) * 2u;
;   struct { bf16x8 vs0, vs1, ks0, ks1, kr; } sr_[1];
;     ...
;   f32x16 pA0, pA1, pB0, pB1; float mnA, mnB, alA, alB; bf16x8 pa0, pa1, pa2, pa3; const int NT = seq / KVBLK;
;     ...
;   SLOAD(0, 0); SWRITE(0, 0); SLOAD(0, KVBLK); LBAR();
.LBB0_1146:
	s_mov_b64 s[18:19], s[0:1]
	s_load_dwordx2 s[30:31], s[26:27], 0x0
	s_waitcnt lgkmcnt(0)
	s_barrier
	s_load_dwordx2 s[38:39], s[18:19], 0x88
	s_mov_b64 s[18:19], s[0:1]
	s_load_dwordx2 s[26:27], s[18:19], 0x88
	s_waitcnt vmcnt(0)
	v_mbcnt_lo_u32_b32 v32, -1, 0
	v_mbcnt_hi_u32_b32 v32, -1, v32
	s_nop 0
	v_add_u32_e32 v33, s7, v32
	v_ashrrev_i32_e32 v0, 6, v33
	s_cmp_lt_u32 s7, 0x100
	s_cbranch_scc1 .Lattn_prio_a
	s_setprio 2
	s_branch .Lattn_prio_done
.Lattn_prio_a:
	s_setprio 0
.Lattn_prio_done:
	s_add_u32 s55, s40, s34
	s_addc_u32 s56, s41, s35
	s_sub_i32 s18, s54, s20
	s_cmp_ge_u32 s54, s20
	s_cselect_b32 s18, s18, s54
	s_xor_b32 s18, s18, s51
	s_sub_i32 s18, s18, s51
	s_ashr_i32 s34, s53, 3
	s_ashr_i32 s35, s34, 31
	s_ashr_i32 s19, s18, 31
	s_and_b32 s51, s53, 7
	s_lshl_b64 s[40:41], s[34:35], s44
	s_lshl_b64 s[18:19], s[18:19], 8
	s_add_u32 s69, s40, s18
	s_addc_u32 s72, s41, s19
	s_add_u32 s53, s30, s28
	s_mul_i32 s18, s72, 0xc00
	s_mul_hi_u32 s19, s69, 0xc00
	s_addc_u32 s54, s31, s29
	s_add_i32 s19, s19, s18
	s_mul_i32 s18, s69, 0xc00
	s_add_u32 s18, s55, s18
	s_addc_u32 s19, s56, s19
	s_mul_i32 s34, s51, 0x180
	s_add_u32 s18, s18, s34
	s_addc_u32 s19, s19, 0
	v_and_b32_e32 v170, 31, v32
	v_lshlrev_b32_e32 v172, 5, v0
	v_bfe_u32 v171, v32, 5, 1
	v_or_b32_e32 v1, v172, v170
	v_mov_b64_e32 v[2:3], s[18:19]
	v_mad_i64_i32 v[2:3], s[18:19], v1, s49, v[2:3]
	v_lshlrev_b32_e32 v164, 4, v171
	v_mov_b32_e32 v165, v193
	v_lshl_add_u64 v[30:31], v[2:3], 0, v[164:165]
	global_load_dwordx4 v[2:5], v[30:31], off offset:256
	global_load_dwordx4 v[6:9], v[30:31], off offset:288
	s_lshl_b64 s[34:35], s[40:41], 12
	s_add_u32 s19, s53, s34
	s_addc_u32 s53, s54, s35
	s_lshl_b32 s18, s51, 9
	s_add_u32 s54, s19, s18
	s_addc_u32 s55, s53, 0
	v_lshlrev_b32_e32 v42, 3, v33
	s_add_u32 s40, s40, s42
	v_and_b32_e32 v18, 0x78, v42
	s_addc_u32 s41, s41, 0
	v_ashrrev_i32_e32 v1, 4, v33
	v_lshlrev_b32_e32 v43, 1, v18
	s_lshl_b64 s[56:57], s[40:41], 7
	s_add_i32 s19, 0, 0x1e000
	s_add_i32 s41, 0, 0x1e800
	v_lshl_or_b32 v68, v1, 12, v43
	v_mov_b32_e32 v69, v193
	v_and_b32_e32 v18, 56, v42
	s_cmp_lg_u32 0, -1
	v_lshl_add_u64 v[72:73], s[54:55], 0, v[68:69]
	v_ashrrev_i32_e32 v44, 3, v33
	s_cselect_b32 s40, 0, 0
	v_lshlrev_b32_e32 v192, 1, v18
	v_add_co_u32_e32 v34, vcc, s79, v72
	s_waitcnt lgkmcnt(0)
	s_add_u32 s38, s38, s56
	v_addc_co_u32_e32 v35, vcc, 0, v73, vcc
	v_lshl_or_b32 v38, v44, 7, v192
	v_mov_b32_e32 v39, v193
	s_addc_u32 s39, s39, s57
	global_load_dwordx4 v[10:13], v[30:31], off offset:320
	global_load_dwordx4 v[14:17], v[30:31], off offset:352
	global_load_dwordx4 v[18:21], v68, s[54:55] offset:256
	global_load_dwordx4 v[22:25], v[34:35], off offset:256
	global_load_dwordx4 v[26:29], v68, s[54:55]
	s_nop 0
	global_load_dwordx4 v[34:37], v[34:35], off
	v_lshl_add_u64 v[70:71], s[38:39], 0, v[38:39]
	s_mov_b32 s38, 0x13000000
	v_add_co_u32_e32 v38, vcc, s38, v70
	v_lshrrev_b32_e32 v45, 1, v33
	s_nop 0
	v_addc_co_u32_e32 v39, vcc, 0, v71, vcc
	global_load_dwordx4 v[38:41], v[38:39], off
	s_nop 0
	global_load_dwordx4 v[124:127], v[30:31], off
	global_load_dwordx4 v[120:123], v[30:31], off offset:32
	global_load_dwordx4 v[116:119], v[30:31], off offset:64
	global_load_dwordx4 v[112:115], v[30:31], off offset:96
	global_load_dwordx4 v[108:111], v[30:31], off offset:128
	global_load_dwordx4 v[104:107], v[30:31], off offset:160
	global_load_dwordx4 v[100:103], v[30:31], off offset:192
	global_load_dwordx4 v[96:99], v[30:31], off offset:224
	v_bfe_u32 v46, v33, 1, 3
	v_bitop3_b32 v47, v45, v171, 7 bitop3:0x6c
	v_lshl_add_u32 v165, v0, 12, s41
	v_bitop3_b32 v48, v171, v46, 2 bitop3:0x36
	v_lshlrev_b32_e32 v47, 4, v47
	v_lshl_add_u32 v0, v170, 7, v165
	v_lshlrev_b32_e32 v48, 4, v48
	v_add_u32_e32 v182, v0, v47
	v_add_u32_e32 v181, v0, v48
	s_mov_b32 s38, 0x13002000
	v_mul_u32_u24_e32 v47, 0x180, v170
	v_or_b32_e32 v80, 0x120, v164
	v_and_b32_e32 v174, 63, v32
	v_lshlrev_b32_e32 v79, 4, v32
	s_mov_b32 s53, s52
	s_mov_b32 s54, s52
	s_mov_b32 s55, s52
	s_waitcnt vmcnt(16)
	ds_write_b128 v182, v[2:5]
	s_waitcnt vmcnt(15)
	ds_write_b128 v181, v[6:9]
	v_bitop3_b32 v2, v171, v46, 4 bitop3:0x36
	v_lshlrev_b32_e32 v2, 4, v2
	v_add_u32_e32 v179, v0, v2
	v_bitop3_b32 v2, v171, v46, 6 bitop3:0x36
	v_lshlrev_b32_e32 v2, 4, v2
	v_add_u32_e32 v177, v0, v2
	v_and_b32_e32 v0, 0xfffff0, v1
	v_lshlrev_b32_e32 v2, 1, v1
	v_and_or_b32 v0, v2, 8, v0
	v_lshrrev_b32_e32 v2, 1, v1
	v_lshrrev_b32_e32 v0, 1, v0
	v_bfe_u32 v3, v42, 5, 2
	v_and_b32_e32 v4, 3, v1
	v_or_b32_e32 v0, v0, v3
	v_and_or_b32 v2, v2, 4, v4
	v_lshlrev_b32_e32 v0, 9, v0
	v_lshlrev_b32_e32 v2, 6, v2
	v_and_b32_e32 v4, 48, v43
	v_or3_b32 v183, v0, v2, v4
	v_add_u32_e32 v0, 32, v1
	v_and_b32_e32 v5, 0xfffff0, v0
	v_lshlrev_b32_e32 v0, 1, v0
	v_and_or_b32 v0, v0, 8, v5
	v_lshrrev_b32_e32 v0, 1, v0
	v_or_b32_e32 v0, v0, v3
	v_lshlrev_b32_e32 v0, 9, v0
	v_or3_b32 v184, v0, v2, v4
	v_mul_lo_u32 v0, v1, s8
	v_and_b32_e32 v1, 0x70, v45
	v_xad_u32 v185, v43, v1, v0
	v_add_u32_e32 v82, 0, v183
	v_add_u32_e32 v83, 0, v184
	v_add_u32_e32 v0, 0, v185
	s_waitcnt vmcnt(14)
	ds_write_b128 v179, v[10:13]
	s_waitcnt vmcnt(13)
	ds_write_b128 v177, v[14:17]
	s_waitcnt vmcnt(12)
	ds_write_b128 v82, v[18:21]
	s_waitcnt vmcnt(11)
	ds_write_b128 v83, v[22:25]
	s_waitcnt vmcnt(10)
	ds_write_b128 v0, v[26:29] offset:49152
	s_waitcnt vmcnt(9)
	ds_write_b128 v0, v[34:37] offset:61440
	v_mul_lo_u32 v0, v44, s8
	v_or_b32_e32 v1, 0x100, v192
	v_and_b32_e32 v2, 0x70, v33
	v_xad_u32 v186, v1, v2, v0
	v_add_u32_e32 v0, 0, v186
	s_waitcnt vmcnt(8)
	ds_write_b128 v0, v[38:41] offset:49152
	v_add_co_u32_e32 v0, vcc, s84, v72
	v_or_b32_e32 v34, 32, v164
	s_nop 0
	v_addc_co_u32_e32 v1, vcc, 0, v73, vcc
	v_add_co_u32_e32 v2, vcc, s85, v72
	v_lshlrev_b32_e32 v46, 4, v46
	s_nop 0
	v_addc_co_u32_e32 v3, vcc, 0, v73, vcc
	global_load_dwordx4 v[48:51], v[0:1], off offset:256
	global_load_dwordx4 v[52:55], v[0:1], off
	global_load_dwordx4 v[60:63], v[2:3], off offset:256
	global_load_dwordx4 v[56:59], v[2:3], off
	v_add_co_u32_e32 v0, vcc, s38, v70
	v_or_b32_e32 v42, 0x100, v164
	s_nop 0
	v_addc_co_u32_e32 v1, vcc, 0, v71, vcc
	global_load_dwordx4 v[64:67], v[0:1], off
	v_lshlrev_b32_e32 v0, 3, v32
	v_and_b32_e32 v78, 0x70, v0
	v_bitop3_b32 v199, v164, v47, v78 bitop3:0xde
	s_waitcnt lgkmcnt(0)
	s_barrier
; __device__ __forceinline__ void qkt(f32x16& p0, f32x16& p1, const char* Ks, const bf16x8* qr, const char* qrl, int r32, int hi) {
;   p0 = f32x16{}; p1 = f32x16{};
; #pragma unroll
;   for (int d0 = 0; d0 < 8; ++d0) { int cb = (d0 * 16 + hi * 8) * 2;
;     bf16x8 b0 = *reinterpret_cast<const bf16x8*>(Ks + KSWZ(r32, cb));
;     bf16x8 b1 = *reinterpret_cast<const bf16x8*>(Ks + KSWZ(32 + r32, cb));
;     p0 = __builtin_amdgcn_mfma_f32_32x32x16_bf16(b0, qr[d0], p0, 0, 0, 0);
;     p1 = __builtin_amdgcn_mfma_f32_32x32x16_bf16(b1, qr[d0], p1, 0, 0, 0); }
; #pragma unroll
;   for (int d0 = 8; d0 < 12; ++d0) { int cb = (d0 * 16 + hi * 8) * 2;
;     bf16x8 b0 = *reinterpret_cast<const bf16x8*>(Ks + KSWZ(r32, cb));
;     bf16x8 b1 = *reinterpret_cast<const bf16x8*>(Ks + KSWZ(32 + r32, cb));
;     bf16x8 qf = *reinterpret_cast<const bf16x8*>(qrl + (((2 * (d0 - 8) + hi) ^ ((r32 >> 1) & 7)) << 4));
;     p0 = __builtin_amdgcn_mfma_f32_32x32x16_bf16(b0, qf, p0, 0, 0, 0);
;     p1 = __builtin_amdgcn_mfma_f32_32x32x16_bf16(b1, qf, p1, 0, 0, 0); }
	v_add_u32_e32 v4, 0, v199
	ds_read_b128 v[0:3], v4 offset:49152
	ds_read_b128 v[16:19], v4 offset:61440
	s_waitcnt vmcnt(12) lgkmcnt(1)
	v_mfma_f32_32x32x16_bf16 v[0:15], v[0:3], v[124:127], 0
	v_bitop3_b32 v205, v34, v47, v78 bitop3:0xde
	v_add_u32_e32 v38, 0, v205
	ds_read_b128 v[34:37], v38 offset:49152
	ds_read_b128 v[38:41], v38 offset:61440
	v_xad_u32 v191, v42, v46, v47
	v_and_b32_e32 v33, 0x3fffffc0, v33
	v_xad_u32 v202, v42, v78, v47
	v_lshl_add_u32 v173, v33, 2, s19
	s_waitcnt lgkmcnt(2)
	v_mfma_f32_32x32x16_bf16 v[16:31], v[16:19], v[124:127], 0
	v_add_u32_e32 v33, 0, v202
	v_xad_u32 v198, v80, v46, v47
	v_xad_u32 v201, v80, v78, v47
	v_lshlrev_b32_e32 v32, 1, v32
	v_and_b32_e32 v32, 32, v32
	s_mov_b32 s19, 0x13004000
	s_mov_b32 s56, s52
	s_waitcnt vmcnt(11) lgkmcnt(1)
	v_mfma_f32_32x32x16_bf16 v[0:15], v[34:37], v[120:123], v[0:15]
	v_or_b32_e32 v34, 64, v164
	v_bitop3_b32 v206, v34, v47, v78 bitop3:0xde
	s_mov_b32 s57, s52
	s_mov_b32 s58, s52
	s_mov_b32 s59, s52
	s_mov_b32 s60, s52
	s_mov_b32 s61, s52
	s_waitcnt lgkmcnt(0)
	v_mfma_f32_32x32x16_bf16 v[16:31], v[38:41], v[120:123], v[16:31]
	v_add_u32_e32 v38, 0, v206
	ds_read_b128 v[34:37], v38 offset:49152
	ds_read_b128 v[38:41], v38 offset:61440
	s_mov_b32 s62, s52
	s_mov_b32 s63, s52
	s_mov_b32 s64, s52
	s_mov_b32 s65, s52
	s_mov_b32 s66, s52
	s_waitcnt vmcnt(10) lgkmcnt(1)
	v_mfma_f32_32x32x16_bf16 v[0:15], v[34:37], v[116:119], v[0:15]
	v_or_b32_e32 v34, 0x60, v164
	v_bitop3_b32 v208, v34, v47, v78 bitop3:0xde
	s_mov_b32 s67, s52
	s_mov_b32 s73, 2
	s_mov_b32 s76, 1
	v_cmp_gt_u32_e64 s[38:39], 32, v174
	v_lshl_add_u32 v175, v170, 2, v173
	s_waitcnt lgkmcnt(0)
	v_mfma_f32_32x32x16_bf16 v[16:31], v[38:41], v[116:119], v[16:31]
	v_add_u32_e32 v38, 0, v208
	ds_read_b128 v[34:37], v38 offset:49152
	ds_read_b128 v[38:41], v38 offset:61440
	v_mov_b32_e32 v176, 0
	s_waitcnt vmcnt(9) lgkmcnt(1)
	v_mfma_f32_32x32x16_bf16 v[0:15], v[34:37], v[112:115], v[0:15]
	v_or_b32_e32 v34, 0x80, v164
	v_xad_u32 v207, v34, v78, v47
	s_waitcnt lgkmcnt(0)
	v_mfma_f32_32x32x16_bf16 v[16:31], v[38:41], v[112:115], v[16:31]
	v_add_u32_e32 v38, 0, v207
	ds_read_b128 v[34:37], v38 offset:49152
	ds_read_b128 v[38:41], v38 offset:61440
	s_waitcnt vmcnt(8) lgkmcnt(1)
	v_mfma_f32_32x32x16_bf16 v[0:15], v[34:37], v[108:111], v[0:15]
	v_or_b32_e32 v34, 0xa0, v164
	v_xad_u32 v204, v34, v78, v47
	s_waitcnt lgkmcnt(0)
	v_mfma_f32_32x32x16_bf16 v[16:31], v[38:41], v[108:111], v[16:31]
	v_add_u32_e32 v38, 0, v204
	ds_read_b128 v[34:37], v38 offset:49152
	ds_read_b128 v[38:41], v38 offset:61440
	s_waitcnt vmcnt(7) lgkmcnt(1)
	v_mfma_f32_32x32x16_bf16 v[0:15], v[34:37], v[104:107], v[0:15]
	v_or_b32_e32 v34, 0xc0, v164
	v_xad_u32 v203, v34, v78, v47
	s_waitcnt lgkmcnt(0)
	v_mfma_f32_32x32x16_bf16 v[16:31], v[38:41], v[104:107], v[16:31]
	v_add_u32_e32 v38, 0, v203
	ds_read_b128 v[34:37], v38 offset:49152
	ds_read_b128 v[38:41], v38 offset:61440
	s_waitcnt vmcnt(6) lgkmcnt(1)
	v_mfma_f32_32x32x16_bf16 v[0:15], v[34:37], v[100:103], v[0:15]
	v_or_b32_e32 v34, 0xe0, v164
	v_xad_u32 v200, v34, v78, v47
	s_waitcnt lgkmcnt(0)
	v_mfma_f32_32x32x16_bf16 v[16:31], v[38:41], v[100:103], v[16:31]
	v_add_u32_e32 v38, 0, v200
	ds_read_b128 v[34:37], v38 offset:49152
	ds_read_b128 v[38:41], v38 offset:61440
	s_waitcnt vmcnt(5) lgkmcnt(1)
	v_mfma_f32_32x32x16_bf16 v[0:15], v[34:37], v[96:99], v[0:15]
	v_add_u32_e32 v34, 0, v191
	ds_read_b128 v[34:37], v34 offset:49152
	s_waitcnt lgkmcnt(1)
	v_mfma_f32_32x32x16_bf16 v[16:31], v[38:41], v[96:99], v[16:31]
	ds_read_b128 v[38:41], v182
	ds_read_b128 v[42:45], v33 offset:61440
	ds_read_b128 v[74:77], v181
	v_lshlrev_b32_e32 v33, 3, v174
	s_waitcnt lgkmcnt(2)
	v_mfma_f32_32x32x16_bf16 v[0:15], v[34:37], v[38:41], v[0:15]
	v_add_u32_e32 v34, 0, v198
	ds_read_b128 v[34:37], v34 offset:49152
	s_waitcnt lgkmcnt(2)
	v_mfma_f32_32x32x16_bf16 v[16:31], v[42:45], v[38:41], v[16:31]
	v_and_b32_e32 v38, 0xc0, v79
	v_and_or_b32 v42, v33, 24, v38
	v_add_u32_e32 v38, 0, v201
	ds_read_b128 v[38:41], v38 offset:61440
	v_and_b32_e32 v33, 0x100, v33
	v_or3_b32 v32, v42, v32, v33
	v_or_b32_e32 v42, 0x140, v164
	v_xad_u32 v187, v42, v46, v47
	v_add_u32_e32 v178, s40, v32
	v_add_u32_e32 v32, 0, v187
	s_waitcnt lgkmcnt(1)
	v_mfma_f32_32x32x16_bf16 v[0:15], v[34:37], v[74:77], v[0:15]
	ds_read_b128 v[32:35], v32 offset:49152
	v_or_b32_e32 v44, 0x160, v164
	v_xad_u32 v189, v42, v78, v47
	v_xad_u32 v188, v44, v46, v47
	v_xad_u32 v190, v44, v78, v47
	s_mov_b64 s[40:41], 0x13008000
	v_lshl_add_u64 v[166:167], v[70:71], 0, s[40:41]
	s_waitcnt lgkmcnt(1)
	v_mfma_f32_32x32x16_bf16 v[16:31], v[38:41], v[74:77], v[16:31]
	ds_read_b128 v[36:39], v179
	v_add_u32_e32 v40, 0, v189
	ds_read_b128 v[40:43], v40 offset:61440
	ds_read_b128 v[74:77], v177
	s_waitcnt lgkmcnt(2)
	v_mfma_f32_32x32x16_bf16 v[0:15], v[32:35], v[36:39], v[0:15]
	v_add_u32_e32 v32, 0, v188
	ds_read_b128 v[32:35], v32 offset:49152
	s_waitcnt lgkmcnt(2)
	v_mfma_f32_32x32x16_bf16 v[16:31], v[40:43], v[36:39], v[16:31]
	v_add_u32_e32 v36, 0, v190
	ds_read_b128 v[78:81], v36 offset:61440
	s_waitcnt lgkmcnt(1)
	v_mfma_f32_32x32x16_bf16 v[0:15], v[32:35], v[74:77], v[0:15]
	v_mov_b64_e32 v[32:33], s[52:53]
	v_mov_b64_e32 v[46:47], s[66:67]
	v_mov_b64_e32 v[34:35], s[54:55]
	v_mov_b64_e32 v[36:37], s[56:57]
	v_mov_b64_e32 v[38:39], s[58:59]
	v_mov_b64_e32 v[40:41], s[60:61]
	v_mov_b64_e32 v[42:43], s[62:63]
	s_waitcnt lgkmcnt(0)
; #define LBAR() do { asm volatile("s_waitcnt lgkmcnt(0)" ::: "memory"); __builtin_amdgcn_s_barrier(); asm volatile("" ::: "memory"); } while (0)
; __device__ __forceinline__ void partialSM(f32x16& p0, f32x16& p1, float& m_reg, float& mn, float& alpha) {
;   constexpr float C = SCALE * 1.4426950408889634f;
;   float pmax = p0[0];
; #pragma unroll
;   for (int r = 1; r < 16; ++r) pmax = fmaxf(pmax, p0[r]);
; #pragma unroll
;   for (int r = 0; r < 16; ++r) pmax = fmaxf(pmax, p1[r]);
;   { auto rr = __builtin_amdgcn_permlane32_swap(__float_as_uint(pmax), __float_as_uint(pmax), false, false);
;     pmax = fmaxf(__uint_as_float(rr[0]), __uint_as_float(rr[1])); }
;   if (__builtin_expect(__all(pmax - m_reg <= THR / SCALE), 1)) { mn = m_reg; alpha = 1.f; }
;   else { mn = fmaxf(m_reg, pmax); alpha = __builtin_amdgcn_exp2f((m_reg - mn) * C); m_reg = mn; }
;   float mnC = -mn * C;
; #pragma unroll
;   for (int r = 0; r < 16; ++r) p0[r] = fmaf(p0[r], C, mnC);
; #pragma unroll
;   for (int r = 0; r < 16; ++r) p1[r] = fmaf(p1[r], C, mnC);
; #pragma unroll
;   for (int r = 0; r < 16; ++r) p0[r] = __builtin_amdgcn_exp2f(p0[r]);
; }
; __device__ __forceinline__ void attn_unit(const bf16_t* __restrict__ Qb, const bf16_t* __restrict__ Kn, const bf16_t* __restrict__ Vh, const bf16_t* __restrict__ Kr,
;                                           bf16_t* GO, int seq, char* lds, const int tid) {
;     ...
;   SWRITE(1, 0); if (2 < NT) SLOAD(0, 2 * KVBLK); LBAR();
	v_mfma_f32_32x32x16_bf16 v[16:31], v[78:81], v[74:77], v[16:31]
	s_nop 2
	v_max_f32_e32 v74, v1, v1
	v_max_f32_e32 v75, v0, v0
	v_max_f32_e32 v74, v75, v74
	v_max3_f32 v74, v74, v2, v3
	v_max3_f32 v74, v74, v4, v5
	v_max3_f32 v74, v74, v6, v7
	v_max3_f32 v74, v74, v8, v9
	v_max3_f32 v74, v74, v10, v11
	v_max3_f32 v74, v74, v12, v13
	v_max3_f32 v74, v74, v14, v15
	v_max3_f32 v74, v74, v16, v17
	v_max3_f32 v74, v74, v18, v19
	v_max3_f32 v74, v74, v20, v21
	v_max3_f32 v74, v74, v22, v23
	v_max3_f32 v74, v74, v24, v25
	v_max3_f32 v74, v74, v26, v27
	v_max3_f32 v74, v74, v28, v29
	v_max3_f32 v76, v74, v30, v31
	v_mov_b32_e32 v74, v76
	s_nop 1
	v_permlane32_swap_b32_e32 v76, v74
	v_max_f32_e32 v77, v74, v74
	v_add_co_u32_e32 v74, vcc, s19, v70
	s_add_i32 s19, 0, 0x12000
	s_nop 0
	v_addc_co_u32_e32 v75, vcc, 0, v71, vcc
	global_load_dwordx4 v[128:131], v[74:75], off
	v_add_co_u32_e32 v74, vcc, s14, v72
	v_mov_b64_e32 v[44:45], s[64:65]
	s_nop 0
	v_addc_co_u32_e32 v75, vcc, 0, v73, vcc
	v_add_co_u32_e32 v72, vcc, s9, v72
	s_nop 1
	v_addc_co_u32_e32 v73, vcc, 0, v73, vcc
	global_load_dwordx4 v[132:135], v[74:75], off
	global_load_dwordx4 v[144:147], v[74:75], off offset:256
	global_load_dwordx4 v[136:139], v[72:73], off
	global_load_dwordx4 v[140:143], v[72:73], off offset:256
	v_max_f32_e32 v72, v76, v76
	v_max_f32_e32 v72, v72, v77
	v_add_f32_e32 v73, 0x7149f2ca, v72
	v_cmp_ge_f32_e32 vcc, s15, v73
	s_waitcnt vmcnt(9)
	ds_write_b128 v82, v[48:51] offset:16384
	s_waitcnt vmcnt(7)
	ds_write_b128 v83, v[60:63] offset:16384
	v_add_u32_e32 v48, s19, v185
	ds_write_b128 v48, v[52:55]
	s_waitcnt vmcnt(6)
	ds_write_b128 v48, v[56:59] offset:12288
	v_add_u32_e32 v48, s19, v186
	s_cmp_eq_u64 vcc, exec
	s_waitcnt vmcnt(5)
	ds_write_b128 v48, v[64:67]
	v_max_f32_e32 v49, 0xf149f2ca, v72
	s_cselect_b64 vcc, -1, 0
	v_mov_b32_e32 v48, 0xf149f2ca
	v_cndmask_b32_e32 v210, v49, v48, vcc
	v_mul_f32_e32 v48, 0xbdd53b94, v210
	v_fmamk_f32 v0, v0, 0x3dd53b94, v48
	v_exp_f32_e32 v225, v0
	v_fmamk_f32 v0, v1, 0x3dd53b94, v48
	v_exp_f32_e32 v228, v0
	v_fmamk_f32 v0, v2, 0x3dd53b94, v48
	v_exp_f32_e32 v226, v0
	v_fmamk_f32 v0, v3, 0x3dd53b94, v48
	v_exp_f32_e32 v229, v0
	v_fmamk_f32 v0, v4, 0x3dd53b94, v48
	v_exp_f32_e32 v227, v0
	v_fmamk_f32 v0, v5, 0x3dd53b94, v48
	v_exp_f32_e32 v230, v0
	v_fmamk_f32 v0, v6, 0x3dd53b94, v48
	v_exp_f32_e32 v223, v0
	v_fmamk_f32 v0, v7, 0x3dd53b94, v48
	v_exp_f32_e32 v224, v0
	v_fmamk_f32 v0, v8, 0x3dd53b94, v48
	v_exp_f32_e32 v219, v0
	v_fmamk_f32 v0, v9, 0x3dd53b94, v48
	v_exp_f32_e32 v221, v0
	v_fmamk_f32 v0, v10, 0x3dd53b94, v48
	s_add_u32 s19, s28, s34
	v_pk_fma_f32 v[156:157], v[22:23], s[16:17], v[48:49] op_sel_hi:[1,0,0]
	v_sub_f32_e32 v22, 0xf149f2ca, v49
	v_exp_f32_e32 v220, v0
	v_fmamk_f32 v0, v11, 0x3dd53b94, v48
	s_addc_u32 s28, s29, s35
	v_mul_f32_e32 v22, 0x3dd53b94, v22
	v_exp_f32_e32 v222, v0
	v_fmamk_f32 v0, v12, 0x3dd53b94, v48
	s_add_u32 s18, s19, s18
	v_exp_f32_e32 v22, v22
	v_exp_f32_e32 v215, v0
	v_fmamk_f32 v0, v13, 0x3dd53b94, v48
	s_addc_u32 s19, s28, 0
	v_pk_fma_f32 v[148:149], v[30:31], s[16:17], v[48:49] op_sel_hi:[1,0,0]
	v_pk_fma_f32 v[150:151], v[28:29], s[16:17], v[48:49] op_sel_hi:[1,0,0]
	v_pk_fma_f32 v[152:153], v[26:27], s[16:17], v[48:49] op_sel_hi:[1,0,0]
	v_pk_fma_f32 v[154:155], v[24:25], s[16:17], v[48:49] op_sel_hi:[1,0,0]
	v_pk_fma_f32 v[158:159], v[20:21], s[16:17], v[48:49] op_sel_hi:[1,0,0]
	v_pk_fma_f32 v[160:161], v[18:19], s[16:17], v[48:49] op_sel_hi:[1,0,0]
	v_pk_fma_f32 v[162:163], v[16:17], s[16:17], v[48:49] op_sel_hi:[1,0,0]
	v_exp_f32_e32 v217, v0
	v_fmamk_f32 v0, v14, 0x3dd53b94, v48
	v_fmac_f32_e32 v48, 0x3dd53b94, v15
	s_add_u32 s18, s30, s18
	v_exp_f32_e32 v216, v0
	v_exp_f32_e32 v218, v48
	s_addc_u32 s19, s31, s19
	s_waitcnt lgkmcnt(0)
	s_barrier
	v_lshl_add_u64 v[0:1], s[18:19], 0, v[68:69]
	s_mov_b64 s[18:19], 0x120100
	v_cndmask_b32_e64 v209, v22, 1.0, vcc
	v_lshl_add_u64 v[168:169], v[0:1], 0, s[18:19]
	v_mov_b64_e32 v[62:63], v[46:47]
	v_mov_b64_e32 v[16:17], v[32:33]
	v_mov_b64_e32 v[0:1], v[32:33]
	v_mov_b64_e32 v[60:61], v[44:45]
	v_mov_b64_e32 v[58:59], v[42:43]
	v_mov_b64_e32 v[56:57], v[40:41]
	v_mov_b64_e32 v[54:55], v[38:39]
	v_mov_b64_e32 v[52:53], v[36:37]
	v_mov_b64_e32 v[50:51], v[34:35]
	v_mov_b64_e32 v[48:49], v[32:33]
	v_mov_b64_e32 v[18:19], v[34:35]
	v_mov_b64_e32 v[20:21], v[36:37]
	v_mov_b64_e32 v[22:23], v[38:39]
	v_mov_b64_e32 v[24:25], v[40:41]
	v_mov_b64_e32 v[26:27], v[42:43]
	v_mov_b64_e32 v[28:29], v[44:45]
	v_mov_b64_e32 v[30:31], v[46:47]
	v_mov_b64_e32 v[2:3], v[34:35]
	v_mov_b64_e32 v[4:5], v[36:37]
	v_mov_b64_e32 v[6:7], v[38:39]
	v_mov_b64_e32 v[8:9], v[40:41]
	v_mov_b64_e32 v[10:11], v[42:43]
	v_mov_b64_e32 v[12:13], v[44:45]
	v_mov_b64_e32 v[14:15], v[46:47]
; __device__ __forceinline__ void finishSM(f32x16& p0, f32x16& p1, float alpha, float& l_reg, bf16x8& pa0, bf16x8& pa1, bf16x8& pa2, bf16x8& pa3) {
; #pragma unroll
;   for (int r = 0; r < 16; ++r) p1[r] = __builtin_amdgcn_exp2f(p1[r]);
;   float ps = 0;
; #pragma unroll
;   for (int r = 0; r < 16; ++r) ps += p0[r];
; #pragma unroll
;   for (int r = 0; r < 16; ++r) ps += p1[r];
;   { auto rr = __builtin_amdgcn_permlane32_swap(__float_as_uint(ps), __float_as_uint(ps), false, false);
;     ps = __uint_as_float(rr[0]) + __uint_as_float(rr[1]); }
;   l_reg = l_reg * alpha + ps;
; __device__ __forceinline__ void qkt(f32x16& p0, f32x16& p1, const char* Ks, const bf16x8* qr, const char* qrl, int r32, int hi) {
;   p0 = f32x16{}; p1 = f32x16{};
; #pragma unroll
;   for (int d0 = 0; d0 < 8; ++d0) { int cb = (d0 * 16 + hi * 8) * 2;
;     bf16x8 b0 = *reinterpret_cast<const bf16x8*>(Ks + KSWZ(r32, cb));
;     bf16x8 b1 = *reinterpret_cast<const bf16x8*>(Ks + KSWZ(32 + r32, cb));
;     p0 = __builtin_amdgcn_mfma_f32_32x32x16_bf16(b0, qr[d0], p0, 0, 0, 0);
;     p1 = __builtin_amdgcn_mfma_f32_32x32x16_bf16(b1, qr[d0], p1, 0, 0, 0); }
; #pragma unroll
;   for (int d0 = 8; d0 < 12; ++d0) { int cb = (d0 * 16 + hi * 8) * 2;
;     bf16x8 b0 = *reinterpret_cast<const bf16x8*>(Ks + KSWZ(r32, cb));
;     bf16x8 b1 = *reinterpret_cast<const bf16x8*>(Ks + KSWZ(32 + r32, cb));
;     bf16x8 qf = *reinterpret_cast<const bf16x8*>(qrl + (((2 * (d0 - 8) + hi) ^ ((r32 >> 1) & 7)) << 4));
;     p0 = __builtin_amdgcn_mfma_f32_32x32x16_bf16(b0, qf, p0, 0, 0, 0);
;     p1 = __builtin_amdgcn_mfma_f32_32x32x16_bf16(b1, qf, p1, 0, 0, 0); }
.LBB0_1151:
	s_sub_i32 s30, s76, 1
	s_cmp_eq_u32 s76, 0
	s_cselect_b32 s30, 2, s30
	s_add_i32 s18, s76, 1
	s_cmp_lg_u32 s76, 2
	s_cselect_b32 s18, s18, 0
	s_mul_i32 s19, s76, 0x6000
	v_add_u32_e32 v194, s19, v199
	ds_read_b128 v[64:67], v194 offset:49152
	ds_read_b128 v[68:71], v194 offset:61440
	v_add_u32_e32 v194, s19, v205
	ds_read_b128 v[232:235], v194 offset:49152
	ds_read_b128 v[236:239], v194 offset:61440
	v_add_u32_e32 v194, s19, v206
	ds_read_b128 v[240:243], v194 offset:49152
	ds_read_b128 v[248:251], v194 offset:61440
	v_exp_f32_e32 v162, v162
	v_add_f32_e32 v211, v225, v228
	v_exp_f32_e32 v163, v163
	v_add_f32_e32 v211, v226, v211
	v_exp_f32_e32 v160, v160
	s_waitcnt lgkmcnt(5)
	v_mfma_f32_32x32x16_bf16 v[80:95], v[64:67], v[124:127], 0
	v_add_f32_e32 v211, v229, v211
	v_exp_f32_e32 v161, v161
	v_add_f32_e32 v211, v227, v211
	s_waitcnt lgkmcnt(4)
	v_mfma_f32_32x32x16_bf16 v[64:79], v[68:71], v[124:127], 0
	v_exp_f32_e32 v158, v158
	v_add_f32_e32 v211, v230, v211
	s_waitcnt lgkmcnt(3)
	v_mfma_f32_32x32x16_bf16 v[80:95], v[232:235], v[120:123], v[80:95]
	v_add_u32_e32 v194, s19, v208
	ds_read_b128 v[232:235], v194 offset:49152
	v_exp_f32_e32 v159, v159
	v_add_f32_e32 v211, v223, v211
	s_waitcnt lgkmcnt(3)
	v_mfma_f32_32x32x16_bf16 v[64:79], v[236:239], v[120:123], v[64:79]
	ds_read_b128 v[236:239], v194 offset:61440
	v_exp_f32_e32 v156, v156
	v_add_f32_e32 v211, v224, v211
	s_waitcnt lgkmcnt(3)
	v_mfma_f32_32x32x16_bf16 v[80:95], v[240:243], v[116:119], v[80:95]
	v_add_u32_e32 v194, s19, v207
	ds_read_b128 v[240:243], v194 offset:49152
	v_exp_f32_e32 v157, v157
	v_add_f32_e32 v211, v219, v211
	s_waitcnt lgkmcnt(3)
	v_mfma_f32_32x32x16_bf16 v[64:79], v[248:251], v[116:119], v[64:79]
	ds_read_b128 v[248:251], v194 offset:61440
	v_exp_f32_e32 v154, v154
	v_add_f32_e32 v211, v221, v211
	s_waitcnt lgkmcnt(3)
	v_mfma_f32_32x32x16_bf16 v[80:95], v[232:235], v[112:115], v[80:95]
	v_add_u32_e32 v194, s19, v204
	ds_read_b128 v[232:235], v194 offset:49152
	v_exp_f32_e32 v155, v155
	v_add_f32_e32 v211, v220, v211
	s_waitcnt lgkmcnt(3)
	v_mfma_f32_32x32x16_bf16 v[64:79], v[236:239], v[112:115], v[64:79]
	ds_read_b128 v[236:239], v194 offset:61440
	v_exp_f32_e32 v152, v152
	v_add_f32_e32 v211, v222, v211
	s_waitcnt lgkmcnt(3)
	v_mfma_f32_32x32x16_bf16 v[80:95], v[240:243], v[108:111], v[80:95]
	v_add_u32_e32 v194, s19, v203
	ds_read_b128 v[240:243], v194 offset:49152
	v_exp_f32_e32 v153, v153
	v_add_f32_e32 v211, v215, v211
	s_waitcnt lgkmcnt(3)
	v_mfma_f32_32x32x16_bf16 v[64:79], v[248:251], v[108:111], v[64:79]
	ds_read_b128 v[248:251], v194 offset:61440
	v_exp_f32_e32 v150, v150
	v_add_f32_e32 v211, v217, v211
	s_waitcnt lgkmcnt(3)
	v_mfma_f32_32x32x16_bf16 v[80:95], v[232:235], v[104:107], v[80:95]
	v_add_u32_e32 v194, s19, v200
	ds_read_b128 v[232:235], v194 offset:49152
	v_exp_f32_e32 v151, v151
	v_add_f32_e32 v211, v216, v211
	s_waitcnt lgkmcnt(3)
	v_mfma_f32_32x32x16_bf16 v[64:79], v[236:239], v[104:107], v[64:79]
	ds_read_b128 v[236:239], v194 offset:61440
	v_exp_f32_e32 v148, v148
	v_add_f32_e32 v211, v218, v211
	s_waitcnt lgkmcnt(3)
	v_mfma_f32_32x32x16_bf16 v[80:95], v[240:243], v[100:103], v[80:95]
	v_add_u32_e32 v194, s19, v191
	ds_read_b128 v[240:243], v194 offset:49152
	v_exp_f32_e32 v149, v149
	v_add_f32_e32 v212, v162, v163
	v_add_f32_e32 v212, v160, v212
	s_waitcnt lgkmcnt(3)
	v_mfma_f32_32x32x16_bf16 v[64:79], v[248:251], v[100:103], v[64:79]
	v_add_u32_e32 v194, s19, v202
	ds_read_b128 v[248:251], v194 offset:61440
	v_add_f32_e32 v212, v161, v212
	v_add_f32_e32 v212, v158, v212
	v_add_f32_e32 v212, v159, v212
	v_add_f32_e32 v212, v156, v212
	s_waitcnt lgkmcnt(3)
	v_mfma_f32_32x32x16_bf16 v[80:95], v[232:235], v[96:99], v[80:95]
	ds_read_b128 v[232:235], v182
	v_add_f32_e32 v212, v157, v212
	v_add_f32_e32 v212, v154, v212
	v_add_f32_e32 v212, v155, v212
	v_add_f32_e32 v212, v152, v212
	s_waitcnt lgkmcnt(3)
	v_mfma_f32_32x32x16_bf16 v[64:79], v[236:239], v[96:99], v[64:79]
	v_add_u32_e32 v194, s19, v198
	ds_read_b128 v[236:239], v194 offset:49152
	v_add_f32_e32 v212, v153, v212
	v_add_f32_e32 v212, v150, v212
	v_add_f32_e32 v212, v151, v212
	v_add_f32_e32 v212, v148, v212
	s_waitcnt lgkmcnt(1)
	v_mfma_f32_32x32x16_bf16 v[80:95], v[240:243], v[232:235], v[80:95]
	v_add_u32_e32 v194, s19, v201
	ds_read_b128 v[240:243], v194 offset:61440
	v_add_f32_e32 v212, v149, v212
	v_add_f32_e32 v211, v211, v212
	v_mov_b32_e32 v212, v211
	v_cvt_pk_bf16_f32 v158, v158, v159
	v_mfma_f32_32x32x16_bf16 v[64:79], v[248:251], v[232:235], v[64:79]
	ds_read_b128 v[248:251], v181
	v_add_u32_e32 v194, s19, v187
	ds_read_b128 v[232:235], v194 offset:49152
	v_cvt_pk_bf16_f32 v159, v156, v157
	v_permlane32_swap_b32_e32 v211, v212
	v_cvt_pk_bf16_f32 v156, v162, v163
	v_cvt_pk_bf16_f32 v157, v160, v161
	s_waitcnt lgkmcnt(1)
	v_mfma_f32_32x32x16_bf16 v[80:95], v[236:239], v[248:251], v[80:95]
	v_add_u32_e32 v194, s19, v189
	ds_read_b128 v[236:239], v194 offset:61440
	v_cvt_pk_bf16_f32 v160, v154, v155
	v_cvt_pk_bf16_f32 v161, v152, v153
	v_cvt_pk_bf16_f32 v162, v150, v151
	v_cvt_pk_bf16_f32 v163, v148, v149
	v_mfma_f32_32x32x16_bf16 v[64:79], v[240:243], v[248:251], v[64:79]
	ds_read_b128 v[240:243], v179
	v_add_u32_e32 v194, s19, v188
	ds_read_b128 v[248:251], v194 offset:49152
	v_add_f32_e32 v211, v211, v212
	v_cvt_pk_bf16_f32 v148, v225, v228
	v_cvt_pk_bf16_f32 v149, v226, v229
	v_cvt_pk_bf16_f32 v150, v227, v230
	s_waitcnt lgkmcnt(1)
; #define SBAR() __builtin_amdgcn_sched_barrier(0)
; template <int D0> __device__ __forceinline__ void pv_one(f32x16& od, int vb, bf16x8 pa0, bf16x8 pa1, bf16x8 pa2, bf16x8 pa3) {
;   const s16x4 l0 = tr_read<v_rd_off(D0, 0, 0)>(vb), h0 = tr_read<v_rd_off(D0, 0, 1)>(vb), l1 = tr_read<v_rd_off(D0, 1, 0)>(vb), h1 = tr_read<v_rd_off(D0, 1, 1)>(vb);
;   const s16x4 l2 = tr_read<v_rd_off(D0, 2, 0)>(vb), h2 = tr_read<v_rd_off(D0, 2, 1)>(vb), l3 = tr_read<v_rd_off(D0, 3, 0)>(vb), h3 = tr_read<v_rd_off(D0, 3, 1)>(vb);
;   asm volatile("s_waitcnt lgkmcnt(0)" ::: "memory"); SBAR();
;     ...
;   od = __builtin_amdgcn_mfma_f32_32x32x16_bf16(pa0, PK(l0, h0), od, 0, 0, 0);
;   od = __builtin_amdgcn_mfma_f32_32x32x16_bf16(pa1, PK(l1, h1), od, 0, 0, 0);
;   od = __builtin_amdgcn_mfma_f32_32x32x16_bf16(pa2, PK(l2, h2), od, 0, 0, 0);
;   od = __builtin_amdgcn_mfma_f32_32x32x16_bf16(pa3, PK(l3, h3), od, 0, 0, 0);
;     ...
; }
; __device__ __forceinline__ void pv_d0(f32x16* o, int vb, bf16x8 pa0, bf16x8 pa1, bf16x8 pa2, bf16x8 pa3) {
;   pv_one<0>(o[0], vb, pa0, pa1, pa2, pa3); pv_one<1>(o[1], vb, pa0, pa1, pa2, pa3); pv_one<2>(o[2], vb, pa0, pa1, pa2, pa3); pv_one<3>(o[3], vb, pa0, pa1, pa2, pa3);
	v_mfma_f32_32x32x16_bf16 v[80:95], v[232:235], v[240:243], v[80:95]
	v_add_u32_e32 v194, s19, v190
	ds_read_b128 v[232:235], v194 offset:61440
	v_cvt_pk_bf16_f32 v151, v223, v224
	v_cvt_pk_bf16_f32 v152, v219, v221
	v_cvt_pk_bf16_f32 v153, v220, v222
	v_cvt_pk_bf16_f32 v154, v215, v217
	v_mfma_f32_32x32x16_bf16 v[64:79], v[236:239], v[240:243], v[64:79]
	ds_read_b128 v[236:239], v177
	v_cvt_pk_bf16_f32 v155, v216, v218
	v_fma_f32 v176, v209, v176, v211
	s_nop 1
	v_permlane32_swap_b32_e32 v156, v158
	s_waitcnt lgkmcnt(0)
	v_mfma_f32_32x32x16_bf16 v[80:95], v[248:251], v[236:239], v[80:95]
	v_permlane32_swap_b32_e32 v157, v159
	v_permlane32_swap_b32_e32 v160, v162
	v_permlane32_swap_b32_e32 v161, v163
	v_permlane32_swap_b32_e32 v148, v150
	v_mfma_f32_32x32x16_bf16 v[64:79], v[232:235], v[236:239], v[64:79]
	v_permlane32_swap_b32_e32 v149, v151
	v_permlane32_swap_b32_e32 v152, v154
	v_permlane32_swap_b32_e32 v153, v155
	s_lshl_b32 s31, s30, 14
	v_add_u32_e32 v180, s31, v178
	ds_read_b64_tr_b16 v[240:241], v180 offset:0
	ds_read_b64_tr_b16 v[242:243], v180 offset:2048
	ds_read_b64_tr_b16 v[248:249], v180 offset:512
	ds_read_b64_tr_b16 v[250:251], v180 offset:2560
	ds_read_b64_tr_b16 v[232:233], v180 offset:1024
	ds_read_b64_tr_b16 v[234:235], v180 offset:3072
	ds_read_b64_tr_b16 v[236:237], v180 offset:1536
	ds_read_b64_tr_b16 v[238:239], v180 offset:3584
	s_lshl_b32 s19, s18, 14
	s_add_i32 s28, s19, 0
	v_add_u32_e32 v231, s28, v183
	s_lshl_b32 s18, s18, 13
	s_waitcnt vmcnt(0)
	ds_write_b128 v231, v[140:143]
	v_add_u32_e32 v140, s28, v184
	s_add_i32 s28, s28, s18
	ds_write_b128 v140, v[144:147]
	v_add_u32_e32 v140, s28, v185
	ds_write_b128 v140, v[136:139] offset:49152
	ds_write_b128 v140, v[132:135] offset:61440
	v_add_u32_e32 v132, s28, v186
	s_mov_b32 s18, 0xfffa0000
	ds_write_b128 v132, v[128:131] offset:49152
	v_add_co_u32_e32 v128, vcc, s18, v168
	s_mov_b32 s18, 0xfffc0000
	s_nop 0
	v_addc_co_u32_e32 v129, vcc, -1, v169, vcc
	v_add_co_u32_e32 v130, vcc, s18, v168
	s_movk_i32 s18, 0xe000
	s_nop 0
	v_addc_co_u32_e32 v131, vcc, -1, v169, vcc
	global_load_dwordx4 v[140:143], v[128:129], off
	global_load_dwordx4 v[136:139], v[128:129], off offset:-256
	global_load_dwordx4 v[144:147], v[130:131], off
	global_load_dwordx4 v[132:135], v[130:131], off offset:-256
	v_add_co_u32_e32 v128, vcc, s18, v166
	s_nop 1
	v_addc_co_u32_e32 v129, vcc, -1, v167, vcc
	global_load_dwordx4 v[128:131], v[128:129], off
	v_max3_f32 v194, v80, v81, v82
	v_max3_f32 v195, v64, v65, v66
	v_max3_f32 v194, v194, v83, v84
	v_max3_f32 v195, v195, v67, v68
	v_max3_f32 v194, v194, v85, v86
	v_max3_f32 v195, v195, v69, v70
	s_waitcnt lgkmcnt(11)
	v_mfma_f32_32x32x16_bf16 v[32:47], v[148:151], v[240:243], v[32:47]
	ds_read_b64_tr_b16 v[240:241], v180 offset:4096
	ds_read_b64_tr_b16 v[242:243], v180 offset:6144
	v_max3_f32 v194, v194, v87, v88
	v_max3_f32 v195, v195, v71, v72
	v_max3_f32 v194, v194, v89, v90
	v_max3_f32 v195, v195, v73, v74
	v_max3_f32 v194, v194, v91, v92
	v_max3_f32 v195, v195, v75, v76
	s_waitcnt lgkmcnt(11)
	v_mfma_f32_32x32x16_bf16 v[48:63], v[148:151], v[248:251], v[48:63]
	ds_read_b64_tr_b16 v[248:249], v180 offset:4608
	ds_read_b64_tr_b16 v[250:251], v180 offset:6656
	v_max3_f32 v194, v194, v93, v94
	v_max3_f32 v195, v195, v77, v78
	v_max3_f32 v194, v194, v95, v195
	v_max_f32_e32 v194, v194, v79
	v_mov_b32_e32 v195, v194
	s_nop 1
	s_waitcnt lgkmcnt(11)
	v_mfma_f32_32x32x16_bf16 v[16:31], v[148:151], v[232:235], v[16:31]
	ds_read_b64_tr_b16 v[232:233], v180 offset:5120
	ds_read_b64_tr_b16 v[234:235], v180 offset:7168
	v_permlane32_swap_b32_e32 v194, v195
	v_max_f32_e32 v194, v194, v195
	v_sub_f32_e32 v195, v194, v210
	v_cmp_ge_f32_e32 vcc, s15, v195
	v_max_f32_e32 v194, v210, v194
	v_sub_f32_e32 v195, v210, v194
	s_waitcnt lgkmcnt(11)
	v_mfma_f32_32x32x16_bf16 v[0:15], v[148:151], v[236:239], v[0:15]
	ds_read_b64_tr_b16 v[236:237], v180 offset:5632
	ds_read_b64_tr_b16 v[238:239], v180 offset:7680
	v_mul_f32_e32 v195, 0x3dd53b94, v195
	v_exp_f32_e32 v195, v195
	s_cmp_eq_u64 vcc, exec
	s_cselect_b64 s[40:41], -1, 0
	v_cndmask_b32_e64 v214, v195, 1.0, s[40:41]
	s_waitcnt lgkmcnt(6)
	v_mfma_f32_32x32x16_bf16 v[32:47], v[152:155], v[240:243], v[32:47]
	ds_read_b64_tr_b16 v[240:241], v180 offset:8192
	ds_read_b64_tr_b16 v[242:243], v180 offset:10240
	v_cndmask_b32_e64 v210, v194, v210, s[40:41]
	v_mul_f32_e32 v194, 0xbdd53b94, v210
	v_fmamk_f32 v80, v80, 0x3dd53b94, v194
	v_fmamk_f32 v81, v81, 0x3dd53b94, v194
	v_fmamk_f32 v82, v82, 0x3dd53b94, v194
	s_waitcnt lgkmcnt(6)
	v_mfma_f32_32x32x16_bf16 v[48:63], v[152:155], v[248:251], v[48:63]
	ds_read_b64_tr_b16 v[248:249], v180 offset:8704
	ds_read_b64_tr_b16 v[250:251], v180 offset:10752
	v_exp_f32_e32 v225, v80
	v_fmamk_f32 v83, v83, 0x3dd53b94, v194
	v_exp_f32_e32 v228, v81
	v_fmamk_f32 v150, v76, 0x3dd53b94, v194
	s_waitcnt lgkmcnt(6)
	v_mfma_f32_32x32x16_bf16 v[16:31], v[152:155], v[232:235], v[16:31]
	ds_read_b64_tr_b16 v[232:233], v180 offset:9216
	ds_read_b64_tr_b16 v[234:235], v180 offset:11264
	v_fmamk_f32 v151, v77, 0x3dd53b94, v194
	v_fmamk_f32 v148, v78, 0x3dd53b94, v194
	v_fmamk_f32 v149, v79, 0x3dd53b94, v194
	v_fmamk_f32 v84, v84, 0x3dd53b94, v194
	v_exp_f32_e32 v226, v82
	s_waitcnt lgkmcnt(6)
	v_mfma_f32_32x32x16_bf16 v[0:15], v[152:155], v[236:239], v[0:15]
	ds_read_b64_tr_b16 v[236:237], v180 offset:9728
	ds_read_b64_tr_b16 v[238:239], v180 offset:11776
	v_fmamk_f32 v85, v85, 0x3dd53b94, v194
	v_exp_f32_e32 v229, v83
	v_fmamk_f32 v86, v86, 0x3dd53b94, v194
	v_exp_f32_e32 v227, v84
	s_waitcnt lgkmcnt(6)
; #define SBAR() __builtin_amdgcn_sched_barrier(0)
; __device__ __forceinline__ void qkt(f32x16& p0, f32x16& p1, const char* Ks, const bf16x8* qr, const char* qrl, int r32, int hi) {
;   p0 = f32x16{}; p1 = f32x16{};
; #pragma unroll
;   for (int d0 = 0; d0 < 8; ++d0) { int cb = (d0 * 16 + hi * 8) * 2;
;     bf16x8 b0 = *reinterpret_cast<const bf16x8*>(Ks + KSWZ(r32, cb));
;     bf16x8 b1 = *reinterpret_cast<const bf16x8*>(Ks + KSWZ(32 + r32, cb));
;     p0 = __builtin_amdgcn_mfma_f32_32x32x16_bf16(b0, qr[d0], p0, 0, 0, 0);
;     p1 = __builtin_amdgcn_mfma_f32_32x32x16_bf16(b1, qr[d0], p1, 0, 0, 0); }
; #pragma unroll
;   for (int d0 = 8; d0 < 12; ++d0) { int cb = (d0 * 16 + hi * 8) * 2;
;     bf16x8 b0 = *reinterpret_cast<const bf16x8*>(Ks + KSWZ(r32, cb));
;     bf16x8 b1 = *reinterpret_cast<const bf16x8*>(Ks + KSWZ(32 + r32, cb));
;     bf16x8 qf = *reinterpret_cast<const bf16x8*>(qrl + (((2 * (d0 - 8) + hi) ^ ((r32 >> 1) & 7)) << 4));
;     p0 = __builtin_amdgcn_mfma_f32_32x32x16_bf16(b0, qf, p0, 0, 0, 0);
;     p1 = __builtin_amdgcn_mfma_f32_32x32x16_bf16(b1, qf, p1, 0, 0, 0); }
; template <int D0> __device__ __forceinline__ void pv_one(f32x16& od, int vb, bf16x8 pa0, bf16x8 pa1, bf16x8 pa2, bf16x8 pa3) {
;   const s16x4 l0 = tr_read<v_rd_off(D0, 0, 0)>(vb), h0 = tr_read<v_rd_off(D0, 0, 1)>(vb), l1 = tr_read<v_rd_off(D0, 1, 0)>(vb), h1 = tr_read<v_rd_off(D0, 1, 1)>(vb);
;   const s16x4 l2 = tr_read<v_rd_off(D0, 2, 0)>(vb), h2 = tr_read<v_rd_off(D0, 2, 1)>(vb), l3 = tr_read<v_rd_off(D0, 3, 0)>(vb), h3 = tr_read<v_rd_off(D0, 3, 1)>(vb);
;   asm volatile("s_waitcnt lgkmcnt(0)" ::: "memory"); SBAR();
;     ...
;   od = __builtin_amdgcn_mfma_f32_32x32x16_bf16(pa0, PK(l0, h0), od, 0, 0, 0);
;   od = __builtin_amdgcn_mfma_f32_32x32x16_bf16(pa1, PK(l1, h1), od, 0, 0, 0);
;   od = __builtin_amdgcn_mfma_f32_32x32x16_bf16(pa2, PK(l2, h2), od, 0, 0, 0);
;   od = __builtin_amdgcn_mfma_f32_32x32x16_bf16(pa3, PK(l3, h3), od, 0, 0, 0);
;     ...
; }
; __device__ __forceinline__ void pv_d0(f32x16* o, int vb, bf16x8 pa0, bf16x8 pa1, bf16x8 pa2, bf16x8 pa3) {
;   pv_one<0>(o[0], vb, pa0, pa1, pa2, pa3); pv_one<1>(o[1], vb, pa0, pa1, pa2, pa3); pv_one<2>(o[2], vb, pa0, pa1, pa2, pa3); pv_one<3>(o[3], vb, pa0, pa1, pa2, pa3);
	v_mfma_f32_32x32x16_bf16 v[32:47], v[156:159], v[240:243], v[32:47]
	ds_read_b64_tr_b16 v[240:241], v180 offset:12288
	ds_read_b64_tr_b16 v[242:243], v180 offset:14336
	v_fmamk_f32 v87, v87, 0x3dd53b94, v194
	v_exp_f32_e32 v230, v85
	v_fmamk_f32 v154, v72, 0x3dd53b94, v194
	v_fmamk_f32 v155, v73, 0x3dd53b94, v194
	v_fmamk_f32 v152, v74, 0x3dd53b94, v194
	s_waitcnt lgkmcnt(6)
	v_mfma_f32_32x32x16_bf16 v[48:63], v[156:159], v[248:251], v[48:63]
	ds_read_b64_tr_b16 v[248:249], v180 offset:12800
	ds_read_b64_tr_b16 v[250:251], v180 offset:14848
	v_fmamk_f32 v153, v75, 0x3dd53b94, v194
	v_fmamk_f32 v88, v88, 0x3dd53b94, v194
	v_exp_f32_e32 v223, v86
	v_fmamk_f32 v89, v89, 0x3dd53b94, v194
	s_waitcnt lgkmcnt(6)
	v_mfma_f32_32x32x16_bf16 v[16:31], v[156:159], v[232:235], v[16:31]
	ds_read_b64_tr_b16 v[232:233], v180 offset:13312
	ds_read_b64_tr_b16 v[234:235], v180 offset:15360
	v_exp_f32_e32 v224, v87
	v_fmamk_f32 v90, v90, 0x3dd53b94, v194
	v_exp_f32_e32 v219, v88
	v_fmamk_f32 v91, v91, 0x3dd53b94, v194
	s_waitcnt lgkmcnt(6)
	v_mfma_f32_32x32x16_bf16 v[0:15], v[156:159], v[236:239], v[0:15]
	ds_read_b64_tr_b16 v[236:237], v180 offset:13824
	ds_read_b64_tr_b16 v[238:239], v180 offset:15872
	v_exp_f32_e32 v221, v89
	v_fmamk_f32 v92, v92, 0x3dd53b94, v194
	v_exp_f32_e32 v220, v90
	v_fmamk_f32 v158, v68, 0x3dd53b94, v194
	s_waitcnt lgkmcnt(6)
	v_mfma_f32_32x32x16_bf16 v[32:47], v[160:163], v[240:243], v[32:47]
	v_fmamk_f32 v159, v69, 0x3dd53b94, v194
	v_fmamk_f32 v156, v70, 0x3dd53b94, v194
	v_fmamk_f32 v157, v71, 0x3dd53b94, v194
	v_fmamk_f32 v93, v93, 0x3dd53b94, v194
	v_exp_f32_e32 v222, v91
	s_waitcnt lgkmcnt(4)
	v_mfma_f32_32x32x16_bf16 v[48:63], v[160:163], v[248:251], v[48:63]
	v_fmamk_f32 v94, v94, 0x3dd53b94, v194
	v_exp_f32_e32 v215, v92
	v_fmamk_f32 v95, v95, 0x3dd53b94, v194
	v_exp_f32_e32 v217, v93
	s_waitcnt lgkmcnt(2)
	v_mfma_f32_32x32x16_bf16 v[16:31], v[160:163], v[232:235], v[16:31]
	v_exp_f32_e32 v216, v94
	v_exp_f32_e32 v218, v95
	s_waitcnt lgkmcnt(0)
	v_mfma_f32_32x32x16_bf16 v[0:15], v[160:163], v[236:239], v[0:15]
	v_fmamk_f32 v162, v64, 0x3dd53b94, v194
	v_fmamk_f32 v163, v65, 0x3dd53b94, v194
	v_fmamk_f32 v160, v66, 0x3dd53b94, v194
	v_fmamk_f32 v161, v67, 0x3dd53b94, v194
	v_cmp_gt_f32_e32 vcc, 1.0, v214
	s_cbranch_vccz .Lattn_skip_rs1
	s_and_saveexec_b64 s[18:19], s[38:39]
	ds_write_b32 v175, v214 offset:128
	s_or_b64 exec, exec, s[18:19]
	s_waitcnt lgkmcnt(0)
	v_add_u32_e32 v194, v173, v164
	ds_read_b128 v[232:235], v194 offset:224
	ds_read_b128 v[236:239], v194 offset:192
	ds_read_b128 v[240:243], v194 offset:160
	ds_read_b128 v[248:251], v194 offset:128
	s_waitcnt lgkmcnt(0)
	v_pk_mul_f32 v[44:45], v[44:45], v[232:233]
	v_pk_mul_f32 v[46:47], v[46:47], v[234:235]
	v_pk_mul_f32 v[40:41], v[40:41], v[236:237]
	v_pk_mul_f32 v[42:43], v[42:43], v[238:239]
	v_pk_mul_f32 v[36:37], v[36:37], v[240:241]
	v_pk_mul_f32 v[38:39], v[38:39], v[242:243]
	v_pk_mul_f32 v[32:33], v[32:33], v[248:249]
	v_pk_mul_f32 v[34:35], v[34:35], v[250:251]
	v_pk_mul_f32 v[60:61], v[60:61], v[232:233]
	v_pk_mul_f32 v[62:63], v[62:63], v[234:235]
	v_pk_mul_f32 v[56:57], v[56:57], v[236:237]
	v_pk_mul_f32 v[58:59], v[58:59], v[238:239]
	v_pk_mul_f32 v[52:53], v[52:53], v[240:241]
	v_pk_mul_f32 v[54:55], v[54:55], v[242:243]
	v_pk_mul_f32 v[48:49], v[48:49], v[248:249]
	v_pk_mul_f32 v[50:51], v[50:51], v[250:251]
	v_pk_mul_f32 v[28:29], v[28:29], v[232:233]
	v_pk_mul_f32 v[30:31], v[30:31], v[234:235]
	v_pk_mul_f32 v[24:25], v[24:25], v[236:237]
	v_pk_mul_f32 v[26:27], v[26:27], v[238:239]
	v_pk_mul_f32 v[20:21], v[20:21], v[240:241]
	v_pk_mul_f32 v[22:23], v[22:23], v[242:243]
	v_pk_mul_f32 v[16:17], v[16:17], v[248:249]
	v_pk_mul_f32 v[18:19], v[18:19], v[250:251]
	v_pk_mul_f32 v[12:13], v[12:13], v[232:233]
	v_pk_mul_f32 v[14:15], v[14:15], v[234:235]
	v_pk_mul_f32 v[8:9], v[8:9], v[236:237]
	v_pk_mul_f32 v[10:11], v[10:11], v[238:239]
	v_pk_mul_f32 v[4:5], v[4:5], v[240:241]
	v_pk_mul_f32 v[6:7], v[6:7], v[242:243]
	v_pk_mul_f32 v[0:1], v[0:1], v[248:249]
	v_pk_mul_f32 v[2:3], v[2:3], v[250:251]
.Lattn_skip_rs1:
	s_waitcnt lgkmcnt(0)
	s_barrier
	v_add_u32_e32 v194, s28, v199
	ds_read_b128 v[64:67], v194 offset:49152
	ds_read_b128 v[68:71], v194 offset:61440
	v_add_u32_e32 v194, s28, v205
	ds_read_b128 v[232:235], v194 offset:49152
	ds_read_b128 v[236:239], v194 offset:61440
	v_add_u32_e32 v194, s28, v206
	ds_read_b128 v[240:243], v194 offset:49152
	ds_read_b128 v[248:251], v194 offset:61440
	v_exp_f32_e32 v162, v162
	v_add_f32_e32 v211, v225, v228
	v_exp_f32_e32 v163, v163
	v_add_f32_e32 v211, v226, v211
	v_exp_f32_e32 v160, v160
	s_waitcnt lgkmcnt(5)
	v_mfma_f32_32x32x16_bf16 v[80:95], v[64:67], v[124:127], 0
	v_add_f32_e32 v211, v229, v211
	v_exp_f32_e32 v161, v161
	v_add_f32_e32 v211, v227, v211
	s_waitcnt lgkmcnt(4)
	v_mfma_f32_32x32x16_bf16 v[64:79], v[68:71], v[124:127], 0
	v_exp_f32_e32 v158, v158
	v_add_f32_e32 v211, v230, v211
	s_waitcnt lgkmcnt(3)
	v_mfma_f32_32x32x16_bf16 v[80:95], v[232:235], v[120:123], v[80:95]
	v_add_u32_e32 v194, s28, v208
	ds_read_b128 v[232:235], v194 offset:49152
	v_exp_f32_e32 v159, v159
	v_add_f32_e32 v211, v223, v211
	s_waitcnt lgkmcnt(3)
	v_mfma_f32_32x32x16_bf16 v[64:79], v[236:239], v[120:123], v[64:79]
	ds_read_b128 v[236:239], v194 offset:61440
	v_exp_f32_e32 v156, v156
	v_add_f32_e32 v211, v224, v211
	s_waitcnt lgkmcnt(3)
	v_mfma_f32_32x32x16_bf16 v[80:95], v[240:243], v[116:119], v[80:95]
	v_add_u32_e32 v194, s28, v207
	ds_read_b128 v[240:243], v194 offset:49152
	v_exp_f32_e32 v157, v157
	v_add_f32_e32 v211, v219, v211
	s_waitcnt lgkmcnt(3)
; #define SBAR() __builtin_amdgcn_sched_barrier(0)
; __device__ __forceinline__ void qkt(f32x16& p0, f32x16& p1, const char* Ks, const bf16x8* qr, const char* qrl, int r32, int hi) {
;   p0 = f32x16{}; p1 = f32x16{};
; #pragma unroll
;   for (int d0 = 0; d0 < 8; ++d0) { int cb = (d0 * 16 + hi * 8) * 2;
;     bf16x8 b0 = *reinterpret_cast<const bf16x8*>(Ks + KSWZ(r32, cb));
;     bf16x8 b1 = *reinterpret_cast<const bf16x8*>(Ks + KSWZ(32 + r32, cb));
;     p0 = __builtin_amdgcn_mfma_f32_32x32x16_bf16(b0, qr[d0], p0, 0, 0, 0);
;     p1 = __builtin_amdgcn_mfma_f32_32x32x16_bf16(b1, qr[d0], p1, 0, 0, 0); }
; #pragma unroll
;   for (int d0 = 8; d0 < 12; ++d0) { int cb = (d0 * 16 + hi * 8) * 2;
;     bf16x8 b0 = *reinterpret_cast<const bf16x8*>(Ks + KSWZ(r32, cb));
;     bf16x8 b1 = *reinterpret_cast<const bf16x8*>(Ks + KSWZ(32 + r32, cb));
;     bf16x8 qf = *reinterpret_cast<const bf16x8*>(qrl + (((2 * (d0 - 8) + hi) ^ ((r32 >> 1) & 7)) << 4));
;     p0 = __builtin_amdgcn_mfma_f32_32x32x16_bf16(b0, qf, p0, 0, 0, 0);
;     p1 = __builtin_amdgcn_mfma_f32_32x32x16_bf16(b1, qf, p1, 0, 0, 0); }
; __device__ __forceinline__ void attn_unit(const bf16_t* __restrict__ Qb, const bf16_t* __restrict__ Kn, const bf16_t* __restrict__ Vh, const bf16_t* __restrict__ Kr,
;                                           bf16_t* GO, int seq, char* lds, const int tid) {
;     ...
;     SWRITE(bp, 0); if (j + 3 < NT) SLOAD(0, (j + 3) * KVBLK); SBAR();
	v_mfma_f32_32x32x16_bf16 v[64:79], v[248:251], v[116:119], v[64:79]
	ds_read_b128 v[248:251], v194 offset:61440
	v_exp_f32_e32 v154, v154
	v_add_f32_e32 v211, v221, v211
	s_waitcnt lgkmcnt(3)
	v_mfma_f32_32x32x16_bf16 v[80:95], v[232:235], v[112:115], v[80:95]
	v_add_u32_e32 v194, s28, v204
	ds_read_b128 v[232:235], v194 offset:49152
	v_exp_f32_e32 v155, v155
	v_add_f32_e32 v211, v220, v211
	s_waitcnt lgkmcnt(3)
	v_mfma_f32_32x32x16_bf16 v[64:79], v[236:239], v[112:115], v[64:79]
	ds_read_b128 v[236:239], v194 offset:61440
	v_exp_f32_e32 v152, v152
	v_add_f32_e32 v211, v222, v211
	s_waitcnt lgkmcnt(3)
	v_mfma_f32_32x32x16_bf16 v[80:95], v[240:243], v[108:111], v[80:95]
	v_add_u32_e32 v194, s28, v203
	ds_read_b128 v[240:243], v194 offset:49152
	v_exp_f32_e32 v153, v153
	v_add_f32_e32 v211, v215, v211
	s_waitcnt lgkmcnt(3)
	v_mfma_f32_32x32x16_bf16 v[64:79], v[248:251], v[108:111], v[64:79]
	ds_read_b128 v[248:251], v194 offset:61440
	v_exp_f32_e32 v150, v150
	v_add_f32_e32 v211, v217, v211
	s_waitcnt lgkmcnt(3)
	v_mfma_f32_32x32x16_bf16 v[80:95], v[232:235], v[104:107], v[80:95]
	v_add_u32_e32 v194, s28, v200
	ds_read_b128 v[232:235], v194 offset:49152
	v_exp_f32_e32 v151, v151
	v_add_f32_e32 v211, v216, v211
	s_waitcnt lgkmcnt(3)
	v_mfma_f32_32x32x16_bf16 v[64:79], v[236:239], v[104:107], v[64:79]
	ds_read_b128 v[236:239], v194 offset:61440
	v_exp_f32_e32 v148, v148
	v_add_f32_e32 v211, v218, v211
	s_waitcnt lgkmcnt(3)
	v_mfma_f32_32x32x16_bf16 v[80:95], v[240:243], v[100:103], v[80:95]
	v_add_u32_e32 v194, s28, v191
	ds_read_b128 v[240:243], v194 offset:49152
	v_exp_f32_e32 v149, v149
	v_add_f32_e32 v212, v162, v163
	v_add_f32_e32 v212, v160, v212
	s_waitcnt lgkmcnt(3)
	v_mfma_f32_32x32x16_bf16 v[64:79], v[248:251], v[100:103], v[64:79]
	v_add_u32_e32 v194, s28, v202
	ds_read_b128 v[248:251], v194 offset:61440
	v_add_f32_e32 v212, v161, v212
	v_add_f32_e32 v212, v158, v212
	v_add_f32_e32 v212, v159, v212
	v_add_f32_e32 v212, v156, v212
	s_waitcnt lgkmcnt(3)
	v_mfma_f32_32x32x16_bf16 v[80:95], v[232:235], v[96:99], v[80:95]
	ds_read_b128 v[232:235], v182
	v_add_f32_e32 v212, v157, v212
	v_add_f32_e32 v212, v154, v212
	v_add_f32_e32 v212, v155, v212
	v_add_f32_e32 v212, v152, v212
	s_waitcnt lgkmcnt(3)
	v_mfma_f32_32x32x16_bf16 v[64:79], v[236:239], v[96:99], v[64:79]
	v_add_u32_e32 v194, s28, v198
	ds_read_b128 v[236:239], v194 offset:49152
	v_add_f32_e32 v212, v153, v212
	v_add_f32_e32 v212, v150, v212
	v_add_f32_e32 v212, v151, v212
	v_add_f32_e32 v212, v148, v212
	s_waitcnt lgkmcnt(1)
	v_mfma_f32_32x32x16_bf16 v[80:95], v[240:243], v[232:235], v[80:95]
	v_add_u32_e32 v194, s28, v201
	ds_read_b128 v[240:243], v194 offset:61440
	v_add_f32_e32 v212, v149, v212
	v_add_f32_e32 v211, v211, v212
	v_mov_b32_e32 v212, v211
	v_cvt_pk_bf16_f32 v158, v158, v159
	v_mfma_f32_32x32x16_bf16 v[64:79], v[248:251], v[232:235], v[64:79]
	ds_read_b128 v[248:251], v181
	v_add_u32_e32 v194, s28, v187
	ds_read_b128 v[232:235], v194 offset:49152
	v_cvt_pk_bf16_f32 v159, v156, v157
	v_permlane32_swap_b32_e32 v211, v212
	v_cvt_pk_bf16_f32 v156, v162, v163
	v_cvt_pk_bf16_f32 v157, v160, v161
	s_waitcnt lgkmcnt(1)
	v_mfma_f32_32x32x16_bf16 v[80:95], v[236:239], v[248:251], v[80:95]
	v_add_u32_e32 v194, s28, v189
	ds_read_b128 v[236:239], v194 offset:61440
	v_cvt_pk_bf16_f32 v160, v154, v155
	v_cvt_pk_bf16_f32 v161, v152, v153
	v_cvt_pk_bf16_f32 v162, v150, v151
	v_cvt_pk_bf16_f32 v163, v148, v149
	v_mfma_f32_32x32x16_bf16 v[64:79], v[240:243], v[248:251], v[64:79]
	ds_read_b128 v[240:243], v179
	v_add_u32_e32 v194, s28, v188
	ds_read_b128 v[248:251], v194 offset:49152
	v_add_f32_e32 v211, v211, v212
	v_cvt_pk_bf16_f32 v148, v225, v228
	v_cvt_pk_bf16_f32 v149, v226, v229
	v_cvt_pk_bf16_f32 v150, v227, v230
	s_waitcnt lgkmcnt(1)
	v_mfma_f32_32x32x16_bf16 v[80:95], v[232:235], v[240:243], v[80:95]
	v_add_u32_e32 v194, s28, v190
	ds_read_b128 v[232:235], v194 offset:61440
	v_cvt_pk_bf16_f32 v151, v223, v224
	v_cvt_pk_bf16_f32 v152, v219, v221
	v_cvt_pk_bf16_f32 v153, v220, v222
	v_cvt_pk_bf16_f32 v154, v215, v217
	v_mfma_f32_32x32x16_bf16 v[64:79], v[236:239], v[240:243], v[64:79]
	ds_read_b128 v[236:239], v177
	v_cvt_pk_bf16_f32 v155, v216, v218
	v_fma_f32 v176, v214, v176, v211
	s_nop 1
	v_permlane32_swap_b32_e32 v156, v158
	s_waitcnt lgkmcnt(0)
	v_mfma_f32_32x32x16_bf16 v[80:95], v[248:251], v[236:239], v[80:95]
	v_permlane32_swap_b32_e32 v157, v159
	v_permlane32_swap_b32_e32 v160, v162
	v_permlane32_swap_b32_e32 v161, v163
	v_permlane32_swap_b32_e32 v148, v150
	v_mfma_f32_32x32x16_bf16 v[64:79], v[232:235], v[236:239], v[64:79]
	v_permlane32_swap_b32_e32 v149, v151
	v_permlane32_swap_b32_e32 v152, v154
	v_permlane32_swap_b32_e32 v153, v155
	v_lshl_add_u32 v231, s76, 14, v178
	ds_read_b64_tr_b16 v[240:241], v231 offset:0
	ds_read_b64_tr_b16 v[242:243], v231 offset:2048
	ds_read_b64_tr_b16 v[248:249], v231 offset:512
	ds_read_b64_tr_b16 v[250:251], v231 offset:2560
	ds_read_b64_tr_b16 v[232:233], v231 offset:1024
	ds_read_b64_tr_b16 v[234:235], v231 offset:3072
	ds_read_b64_tr_b16 v[236:237], v231 offset:1536
	ds_read_b64_tr_b16 v[238:239], v231 offset:3584
	s_add_i32 s18, s31, 0
	v_add_u32_e32 v194, s18, v183
	s_waitcnt vmcnt(4)
	ds_write_b128 v194, v[140:143]
	v_add_u32_e32 v194, s18, v184
	s_mul_i32 s18, s30, 0x6000
	s_add_i32 s34, s18, 0
	s_add_i32 s73, s73, 2
	s_cmp_ge_u32 s73, s45
	s_waitcnt vmcnt(2)
	ds_write_b128 v194, v[144:147]
	v_add_u32_e32 v194, s34, v185
	s_cselect_b64 s[28:29], -1, 0
	ds_write_b128 v194, v[136:139] offset:49152
	s_waitcnt vmcnt(1)
	ds_write_b128 v194, v[132:135] offset:61440
	v_add_u32_e32 v194, s34, v186
	s_and_b64 vcc, exec, s[28:29]
	s_waitcnt vmcnt(0)
	ds_write_b128 v194, v[128:131] offset:49152
	s_cbranch_vccnz .LBB0_1157
	v_add_co_u32_e32 v128, vcc, 0xfffe0000, v168
	s_nop 1
	v_addc_co_u32_e32 v129, vcc, -1, v169, vcc
	global_load_dwordx4 v[140:143], v[128:129], off
	global_load_dwordx4 v[136:139], v[128:129], off offset:-256
	global_load_dwordx4 v[144:147], v[168:169], off
	global_load_dwordx4 v[132:135], v[168:169], off offset:-256
	s_nop 0
	global_load_dwordx4 v[128:131], v[166:167], off
; #define SBAR() __builtin_amdgcn_sched_barrier(0)
; __device__ __forceinline__ void partialSM(f32x16& p0, f32x16& p1, float& m_reg, float& mn, float& alpha) {
;   constexpr float C = SCALE * 1.4426950408889634f;
;   float pmax = p0[0];
; #pragma unroll
;   for (int r = 1; r < 16; ++r) pmax = fmaxf(pmax, p0[r]);
; #pragma unroll
;   for (int r = 0; r < 16; ++r) pmax = fmaxf(pmax, p1[r]);
;   { auto rr = __builtin_amdgcn_permlane32_swap(__float_as_uint(pmax), __float_as_uint(pmax), false, false);
;     pmax = fmaxf(__uint_as_float(rr[0]), __uint_as_float(rr[1])); }
;   if (__builtin_expect(__all(pmax - m_reg <= THR / SCALE), 1)) { mn = m_reg; alpha = 1.f; }
;   else { mn = fmaxf(m_reg, pmax); alpha = __builtin_amdgcn_exp2f((m_reg - mn) * C); m_reg = mn; }
;   float mnC = -mn * C;
; #pragma unroll
;   for (int r = 0; r < 16; ++r) p0[r] = fmaf(p0[r], C, mnC);
; #pragma unroll
;   for (int r = 0; r < 16; ++r) p1[r] = fmaf(p1[r], C, mnC);
; #pragma unroll
;   for (int r = 0; r < 16; ++r) p0[r] = __builtin_amdgcn_exp2f(p0[r]);
; }
; template <int D0> __device__ __forceinline__ void pv_one(f32x16& od, int vb, bf16x8 pa0, bf16x8 pa1, bf16x8 pa2, bf16x8 pa3) {
;   const s16x4 l0 = tr_read<v_rd_off(D0, 0, 0)>(vb), h0 = tr_read<v_rd_off(D0, 0, 1)>(vb), l1 = tr_read<v_rd_off(D0, 1, 0)>(vb), h1 = tr_read<v_rd_off(D0, 1, 1)>(vb);
;   const s16x4 l2 = tr_read<v_rd_off(D0, 2, 0)>(vb), h2 = tr_read<v_rd_off(D0, 2, 1)>(vb), l3 = tr_read<v_rd_off(D0, 3, 0)>(vb), h3 = tr_read<v_rd_off(D0, 3, 1)>(vb);
;   asm volatile("s_waitcnt lgkmcnt(0)" ::: "memory"); SBAR();
;     ...
;   od = __builtin_amdgcn_mfma_f32_32x32x16_bf16(pa0, PK(l0, h0), od, 0, 0, 0);
;   od = __builtin_amdgcn_mfma_f32_32x32x16_bf16(pa1, PK(l1, h1), od, 0, 0, 0);
;   od = __builtin_amdgcn_mfma_f32_32x32x16_bf16(pa2, PK(l2, h2), od, 0, 0, 0);
;   od = __builtin_amdgcn_mfma_f32_32x32x16_bf16(pa3, PK(l3, h3), od, 0, 0, 0);
;     ...
; }
; __device__ __forceinline__ void pv_d0(f32x16* o, int vb, bf16x8 pa0, bf16x8 pa1, bf16x8 pa2, bf16x8 pa3) {
;   pv_one<0>(o[0], vb, pa0, pa1, pa2, pa3); pv_one<1>(o[1], vb, pa0, pa1, pa2, pa3); pv_one<2>(o[2], vb, pa0, pa1, pa2, pa3); pv_one<3>(o[3], vb, pa0, pa1, pa2, pa3);
.LBB0_1157:
	v_max3_f32 v194, v80, v81, v82
	v_max3_f32 v195, v64, v65, v66
	v_max3_f32 v194, v194, v83, v84
	v_max3_f32 v195, v195, v67, v68
	v_max3_f32 v194, v194, v85, v86
	v_max3_f32 v195, v195, v69, v70
	s_waitcnt lgkmcnt(11)
	v_mfma_f32_32x32x16_bf16 v[32:47], v[148:151], v[240:243], v[32:47]
	ds_read_b64_tr_b16 v[240:241], v231 offset:4096
	ds_read_b64_tr_b16 v[242:243], v231 offset:6144
	v_max3_f32 v194, v194, v87, v88
	v_max3_f32 v195, v195, v71, v72
	v_max3_f32 v194, v194, v89, v90
	v_max3_f32 v195, v195, v73, v74
	v_max3_f32 v194, v194, v91, v92
	v_max3_f32 v195, v195, v75, v76
	s_waitcnt lgkmcnt(11)
	v_mfma_f32_32x32x16_bf16 v[48:63], v[148:151], v[248:251], v[48:63]
	ds_read_b64_tr_b16 v[248:249], v231 offset:4608
	ds_read_b64_tr_b16 v[250:251], v231 offset:6656
	v_max3_f32 v194, v194, v93, v94
	v_max3_f32 v195, v195, v77, v78
	v_max3_f32 v194, v194, v95, v195
	v_max_f32_e32 v194, v194, v79
	v_mov_b32_e32 v195, v194
	s_nop 1
	s_waitcnt lgkmcnt(11)
	v_mfma_f32_32x32x16_bf16 v[16:31], v[148:151], v[232:235], v[16:31]
	ds_read_b64_tr_b16 v[232:233], v231 offset:5120
	ds_read_b64_tr_b16 v[234:235], v231 offset:7168
	v_permlane32_swap_b32_e32 v194, v195
	v_max_f32_e32 v194, v194, v195
	v_sub_f32_e32 v195, v194, v210
	v_cmp_ge_f32_e32 vcc, s15, v195
	v_max_f32_e32 v194, v210, v194
	v_sub_f32_e32 v195, v210, v194
	s_waitcnt lgkmcnt(11)
	v_mfma_f32_32x32x16_bf16 v[0:15], v[148:151], v[236:239], v[0:15]
	ds_read_b64_tr_b16 v[236:237], v231 offset:5632
	ds_read_b64_tr_b16 v[238:239], v231 offset:7680
	v_mul_f32_e32 v195, 0x3dd53b94, v195
	v_exp_f32_e32 v195, v195
	s_cmp_eq_u64 vcc, exec
	s_cselect_b64 s[40:41], -1, 0
	v_cndmask_b32_e64 v213, v195, 1.0, s[40:41]
	s_waitcnt lgkmcnt(6)
	v_mfma_f32_32x32x16_bf16 v[32:47], v[152:155], v[240:243], v[32:47]
	ds_read_b64_tr_b16 v[240:241], v231 offset:8192
	ds_read_b64_tr_b16 v[242:243], v231 offset:10240
	v_cndmask_b32_e64 v210, v194, v210, s[40:41]
	v_mul_f32_e32 v194, 0xbdd53b94, v210
	v_fmamk_f32 v80, v80, 0x3dd53b94, v194
	v_fmamk_f32 v81, v81, 0x3dd53b94, v194
	v_fmamk_f32 v82, v82, 0x3dd53b94, v194
	s_waitcnt lgkmcnt(6)
	v_mfma_f32_32x32x16_bf16 v[48:63], v[152:155], v[248:251], v[48:63]
	ds_read_b64_tr_b16 v[248:249], v231 offset:8704
	ds_read_b64_tr_b16 v[250:251], v231 offset:10752
	v_exp_f32_e32 v225, v80
	v_fmamk_f32 v83, v83, 0x3dd53b94, v194
	v_exp_f32_e32 v228, v81
	v_fmamk_f32 v150, v76, 0x3dd53b94, v194
	s_waitcnt lgkmcnt(6)
	v_mfma_f32_32x32x16_bf16 v[16:31], v[152:155], v[232:235], v[16:31]
	ds_read_b64_tr_b16 v[232:233], v231 offset:9216
	ds_read_b64_tr_b16 v[234:235], v231 offset:11264
	v_fmamk_f32 v151, v77, 0x3dd53b94, v194
	v_fmamk_f32 v148, v78, 0x3dd53b94, v194
	v_fmamk_f32 v149, v79, 0x3dd53b94, v194
	v_fmamk_f32 v84, v84, 0x3dd53b94, v194
	v_exp_f32_e32 v226, v82
	s_waitcnt lgkmcnt(6)
	v_mfma_f32_32x32x16_bf16 v[0:15], v[152:155], v[236:239], v[0:15]
	ds_read_b64_tr_b16 v[236:237], v231 offset:9728
	ds_read_b64_tr_b16 v[238:239], v231 offset:11776
	v_fmamk_f32 v85, v85, 0x3dd53b94, v194
	v_exp_f32_e32 v229, v83
	v_fmamk_f32 v86, v86, 0x3dd53b94, v194
	v_exp_f32_e32 v227, v84
	s_waitcnt lgkmcnt(6)
	v_mfma_f32_32x32x16_bf16 v[32:47], v[156:159], v[240:243], v[32:47]
	ds_read_b64_tr_b16 v[240:241], v231 offset:12288
	ds_read_b64_tr_b16 v[242:243], v231 offset:14336
	v_fmamk_f32 v87, v87, 0x3dd53b94, v194
	v_exp_f32_e32 v230, v85
	v_fmamk_f32 v154, v72, 0x3dd53b94, v194
	v_fmamk_f32 v155, v73, 0x3dd53b94, v194
	v_fmamk_f32 v152, v74, 0x3dd53b94, v194
	s_waitcnt lgkmcnt(6)
	v_mfma_f32_32x32x16_bf16 v[48:63], v[156:159], v[248:251], v[48:63]
	ds_read_b64_tr_b16 v[248:249], v231 offset:12800
	ds_read_b64_tr_b16 v[250:251], v231 offset:14848
	v_fmamk_f32 v153, v75, 0x3dd53b94, v194
	v_fmamk_f32 v88, v88, 0x3dd53b94, v194
	v_exp_f32_e32 v223, v86
	v_fmamk_f32 v89, v89, 0x3dd53b94, v194
	s_waitcnt lgkmcnt(6)
	v_mfma_f32_32x32x16_bf16 v[16:31], v[156:159], v[232:235], v[16:31]
	ds_read_b64_tr_b16 v[232:233], v231 offset:13312
	ds_read_b64_tr_b16 v[234:235], v231 offset:15360
	v_exp_f32_e32 v224, v87
	v_fmamk_f32 v90, v90, 0x3dd53b94, v194
	v_exp_f32_e32 v219, v88
	v_fmamk_f32 v91, v91, 0x3dd53b94, v194
	s_waitcnt lgkmcnt(6)
	v_mfma_f32_32x32x16_bf16 v[0:15], v[156:159], v[236:239], v[0:15]
	ds_read_b64_tr_b16 v[236:237], v231 offset:13824
	ds_read_b64_tr_b16 v[238:239], v231 offset:15872
	v_exp_f32_e32 v221, v89
	v_fmamk_f32 v92, v92, 0x3dd53b94, v194
	v_exp_f32_e32 v220, v90
	v_fmamk_f32 v158, v68, 0x3dd53b94, v194
	s_waitcnt lgkmcnt(6)
	v_mfma_f32_32x32x16_bf16 v[32:47], v[160:163], v[240:243], v[32:47]
	v_fmamk_f32 v159, v69, 0x3dd53b94, v194
	v_fmamk_f32 v156, v70, 0x3dd53b94, v194
	v_fmamk_f32 v157, v71, 0x3dd53b94, v194
	v_fmamk_f32 v93, v93, 0x3dd53b94, v194
	v_exp_f32_e32 v222, v91
	s_waitcnt lgkmcnt(4)
	v_mfma_f32_32x32x16_bf16 v[48:63], v[160:163], v[248:251], v[48:63]
	v_fmamk_f32 v94, v94, 0x3dd53b94, v194
	v_exp_f32_e32 v215, v92
	v_fmamk_f32 v95, v95, 0x3dd53b94, v194
	v_exp_f32_e32 v217, v93
	s_waitcnt lgkmcnt(2)
	v_mfma_f32_32x32x16_bf16 v[16:31], v[160:163], v[232:235], v[16:31]
	v_exp_f32_e32 v216, v94
	v_exp_f32_e32 v218, v95
	s_waitcnt lgkmcnt(0)
	v_mfma_f32_32x32x16_bf16 v[0:15], v[160:163], v[236:239], v[0:15]
	v_fmamk_f32 v162, v64, 0x3dd53b94, v194
	v_fmamk_f32 v163, v65, 0x3dd53b94, v194
	v_fmamk_f32 v160, v66, 0x3dd53b94, v194
	v_fmamk_f32 v161, v67, 0x3dd53b94, v194
	v_cmp_gt_f32_e32 vcc, 1.0, v213
	s_cbranch_vccz .Lattn_skip_rs2
	s_and_saveexec_b64 s[18:19], s[38:39]
	ds_write_b32 v175, v213 offset:128
	s_or_b64 exec, exec, s[18:19]
	s_waitcnt lgkmcnt(0)
	v_add_u32_e32 v194, v173, v164
	ds_read_b128 v[232:235], v194 offset:224
	ds_read_b128 v[236:239], v194 offset:192
	ds_read_b128 v[240:243], v194 offset:160
	ds_read_b128 v[248:251], v194 offset:128
	s_waitcnt lgkmcnt(0)
	v_pk_mul_f32 v[44:45], v[44:45], v[232:233]
	v_pk_mul_f32 v[46:47], v[46:47], v[234:235]
	v_pk_mul_f32 v[40:41], v[40:41], v[236:237]
	v_pk_mul_f32 v[42:43], v[42:43], v[238:239]
	v_pk_mul_f32 v[36:37], v[36:37], v[240:241]
	v_pk_mul_f32 v[38:39], v[38:39], v[242:243]
	v_pk_mul_f32 v[32:33], v[32:33], v[248:249]
	v_pk_mul_f32 v[34:35], v[34:35], v[250:251]
	v_pk_mul_f32 v[60:61], v[60:61], v[232:233]
	v_pk_mul_f32 v[62:63], v[62:63], v[234:235]
	v_pk_mul_f32 v[56:57], v[56:57], v[236:237]
	v_pk_mul_f32 v[58:59], v[58:59], v[238:239]
	v_pk_mul_f32 v[52:53], v[52:53], v[240:241]
	v_pk_mul_f32 v[54:55], v[54:55], v[242:243]
	v_pk_mul_f32 v[48:49], v[48:49], v[248:249]
	v_pk_mul_f32 v[50:51], v[50:51], v[250:251]
	v_pk_mul_f32 v[28:29], v[28:29], v[232:233]
	v_pk_mul_f32 v[30:31], v[30:31], v[234:235]
	v_pk_mul_f32 v[24:25], v[24:25], v[236:237]
	v_pk_mul_f32 v[26:27], v[26:27], v[238:239]
	v_pk_mul_f32 v[20:21], v[20:21], v[240:241]
	v_pk_mul_f32 v[22:23], v[22:23], v[242:243]
	v_pk_mul_f32 v[16:17], v[16:17], v[248:249]
	v_pk_mul_f32 v[18:19], v[18:19], v[250:251]
	v_pk_mul_f32 v[12:13], v[12:13], v[232:233]
	v_pk_mul_f32 v[14:15], v[14:15], v[234:235]
	v_pk_mul_f32 v[8:9], v[8:9], v[236:237]
	v_pk_mul_f32 v[10:11], v[10:11], v[238:239]
	v_pk_mul_f32 v[4:5], v[4:5], v[240:241]
	v_pk_mul_f32 v[6:7], v[6:7], v[242:243]
	v_pk_mul_f32 v[0:1], v[0:1], v[248:249]
	v_pk_mul_f32 v[2:3], v[2:3], v[250:251]
